# grid barrier: every workgroup waits on the monotonic top-level arrival counter (>= (gen+1)*nx) instead of the generation word bumped by the last leader; generation bump and unused per-XCD generation a
# baseline (speedup 1.0000x reference)
.LBB0_88:
	s_or_b64 exec, exec, s[14:15]
	v_cvt_f32_u32_e32 v6, v4
	s_waitcnt vmcnt(0)
	v_readfirstlane_b32 s12, v5
	v_sub_u32_e32 v5, 0, v4
	v_rcp_iflag_f32_e32 v6, v6
	v_add_u32_e32 v7, s12, v3
	v_mul_f32_e32 v6, 0x4f7ffffe, v6
	v_cvt_u32_f32_e32 v6, v6
	v_mul_lo_u32 v3, v5, v6
	v_mul_hi_u32 v3, v6, v3
	v_add_u32_e32 v3, v6, v3
	v_mul_hi_u32 v3, v7, v3
	v_mul_lo_u32 v5, v3, v4
	v_sub_u32_e32 v5, v7, v5
	v_add_u32_e32 v6, 1, v3
	v_cmp_ge_u32_e32 vcc, v5, v4
	s_nop 1
	v_cndmask_b32_e32 v3, v3, v6, vcc
	v_sub_u32_e32 v6, v5, v4
	v_cndmask_b32_e32 v5, v5, v6, vcc
	v_add_u32_e32 v6, 1, v3
	v_cmp_ge_u32_e32 vcc, v5, v4
	v_add_u32_e32 v5, 1, v7
	s_nop 0
	v_cndmask_b32_e32 v3, v3, v6, vcc
	v_mul_lo_u32 v6, v4, v3
	v_add_u32_e32 v4, v6, v4
	v_cmp_ne_u32_e32 vcc, v5, v4
	s_and_saveexec_b64 s[12:13], vcc
	s_xor_b64 s[12:13], exec, s[12:13]
	s_cbranch_execz .LBB0_102
	s_waitcnt lgkmcnt(0)
	v_add_u32_e32 v3, 1, v3
	v_mul_lo_u32 v3, v3, v2
	v_mov_b32_e32 v2, 0
	s_add_u32 s18, s66, 0x1bc3400
	s_addc_u32 s19, s67, 0
	global_load_dword v2, v2, s[18:19] sc1
	s_waitcnt vmcnt(0)
	v_cmp_lt_u32_e32 vcc, v2, v3
	s_and_saveexec_b64 s[14:15], vcc
	s_cbranch_execz .LBB0_101
	s_add_u32 s16, s66, 0x1bc0200
	s_addc_u32 s17, s67, 0
	s_mov_b32 s30, 1
	s_mov_b64 s[20:21], 0
	v_mov_b32_e32 v2, 0
	s_branch .LBB0_92

.LBB0_96:
	global_load_dword v4, v2, s[18:19] sc1
	s_add_i32 s30, s30, 1
	s_mov_b64 s[26:27], -1
	s_waitcnt vmcnt(0)
	v_cmp_ge_u32_e32 vcc, v4, v3
	s_orn2_b64 s[24:25], vcc, exec
	s_branch .LBB0_91

.LBB0_105:
	s_or_b64 exec, exec, s[14:15]
	v_cvt_f32_u32_e32 v5, v2
	s_waitcnt vmcnt(0)
	v_readfirstlane_b32 s12, v4
	s_add_u32 s14, s66, 0x1bc3400
	s_addc_u32 s15, s67, 0
	v_rcp_iflag_f32_e32 v5, v5
	v_add_u32_e32 v3, s12, v3
	v_add_u32_e32 v6, 1, v3
	s_mov_b64 s[16:17], -1
	v_mul_f32_e32 v4, 0x4f7ffffe, v5
	v_cvt_u32_f32_e32 v4, v4
	v_sub_u32_e32 v5, 0, v2
	v_mul_lo_u32 v5, v5, v4
	v_mul_hi_u32 v5, v4, v5
	v_add_u32_e32 v4, v4, v5
	v_mul_hi_u32 v4, v3, v4
	v_mul_lo_u32 v5, v4, v2
	v_sub_u32_e32 v3, v3, v5
	v_add_u32_e32 v7, 1, v4
	v_cmp_ge_u32_e32 vcc, v3, v2
	v_sub_u32_e32 v5, v3, v2
	s_nop 0
	v_cndmask_b32_e32 v4, v4, v7, vcc
	v_cndmask_b32_e32 v3, v3, v5, vcc
	v_add_u32_e32 v5, 1, v4
	v_cmp_ge_u32_e32 vcc, v3, v2
	s_nop 1
	v_cndmask_b32_e32 v4, v4, v5, vcc
	v_mul_lo_u32 v3, v2, v4
	v_add_u32_e32 v2, v3, v2
	v_cmp_ne_u32_e32 vcc, v6, v2
	v_mov_b32_e32 v4, v2
	v_mov_b64_e32 v[2:3], s[14:15]
	s_and_saveexec_b64 s[12:13], vcc
	s_cbranch_execz .LBB0_117
	v_mov_b32_e32 v2, 0
	global_load_dword v3, v2, s[14:15] sc1
	s_mov_b64 s[20:21], 0
	s_waitcnt vmcnt(0)
	v_cmp_lt_u32_e32 vcc, v3, v4
	s_and_saveexec_b64 s[18:19], vcc
	s_cbranch_execz .LBB0_116
	s_add_u32 s16, s66, 0x1bc0200
	s_addc_u32 s17, s67, 0
	s_mov_b32 s30, 1
	s_branch .LBB0_109

.LBB0_113:
	global_load_dword v3, v2, s[14:15] sc1
	s_add_i32 s30, s30, 1
	s_mov_b64 s[24:25], -1
	s_waitcnt vmcnt(0)
	v_cmp_ge_u32_e32 vcc, v3, v4
	s_orn2_b64 s[28:29], vcc, exec
	s_branch .LBB0_108

.LBB0_117:
	s_or_b64 exec, exec, s[12:13]
	s_and_saveexec_b64 s[12:13], s[16:17]
	s_cbranch_execz .LBB0_119
.LBB0_119:
	s_or_b64 exec, exec, s[12:13]
	s_mov_b64 s[12:13], exec
	v_mbcnt_lo_u32_b32 v2, s12, 0
	v_mbcnt_hi_u32_b32 v2, s13, v2
	v_cmp_eq_u32_e32 vcc, 0, v2
	s_waitcnt vmcnt(0)
	s_and_saveexec_b64 s[14:15], vcc
	s_cbranch_execz .LBB0_121
	s_bcnt1_i32_b64 s12, s[12:13]
	v_mov_b32_e32 v2, 0x2000
	v_mov_b32_e32 v3, s12
.LBB0_121:
	s_or_b64 exec, exec, s[14:15]
	s_waitcnt vmcnt(0)

.LBB0_189:
	s_or_b64 exec, exec, s[12:13]
	s_and_saveexec_b64 s[12:13], s[16:17]
	s_cbranch_execz .LBB0_191
.LBB0_191:
	s_or_b64 exec, exec, s[12:13]
	s_mov_b64 s[12:13], exec
	v_mbcnt_lo_u32_b32 v2, s12, 0
	v_mbcnt_hi_u32_b32 v2, s13, v2
	v_cmp_eq_u32_e32 vcc, 0, v2
	s_waitcnt vmcnt(0)
	s_and_saveexec_b64 s[14:15], vcc
	s_cbranch_execz .LBB0_193
	s_bcnt1_i32_b64 s12, s[12:13]
	v_mov_b32_e32 v2, 0x2000
	v_mov_b32_e32 v3, s12
.LBB0_193:
	s_or_b64 exec, exec, s[14:15]
	s_waitcnt vmcnt(0)

.LBB0_274:
	s_or_b64 exec, exec, s[12:13]
	s_and_saveexec_b64 s[12:13], s[16:17]
	s_cbranch_execz .LBB0_276
.LBB0_276:
	s_or_b64 exec, exec, s[12:13]
	s_mov_b64 s[12:13], exec
	v_mbcnt_lo_u32_b32 v2, s12, 0
	v_mbcnt_hi_u32_b32 v2, s13, v2
	v_cmp_eq_u32_e32 vcc, 0, v2
	s_waitcnt vmcnt(0)
	s_and_saveexec_b64 s[14:15], vcc
	s_cbranch_execz .LBB0_278
	s_bcnt1_i32_b64 s12, s[12:13]
	v_mov_b32_e32 v2, 0x2000
	v_mov_b32_e32 v3, s12
.LBB0_278:
	s_or_b64 exec, exec, s[14:15]
	s_waitcnt vmcnt(0)

.LBB0_530:
	s_or_b64 exec, exec, s[12:13]
	v_cvt_f32_u32_e32 v6, v4
	s_waitcnt vmcnt(0)
	v_readfirstlane_b32 s10, v5
	v_sub_u32_e32 v5, 0, v4
	v_rcp_iflag_f32_e32 v6, v6
	v_add_u32_e32 v7, s10, v3
	v_mul_f32_e32 v6, 0x4f7ffffe, v6
	v_cvt_u32_f32_e32 v6, v6
	v_mul_lo_u32 v3, v5, v6
	v_mul_hi_u32 v3, v6, v3
	v_add_u32_e32 v3, v6, v3
	v_mul_hi_u32 v3, v7, v3
	v_mul_lo_u32 v5, v3, v4
	v_sub_u32_e32 v5, v7, v5
	v_add_u32_e32 v6, 1, v3
	v_cmp_ge_u32_e32 vcc, v5, v4
	s_nop 1
	v_cndmask_b32_e32 v3, v3, v6, vcc
	v_sub_u32_e32 v6, v5, v4
	v_cndmask_b32_e32 v5, v5, v6, vcc
	v_add_u32_e32 v6, 1, v3
	v_cmp_ge_u32_e32 vcc, v5, v4
	v_add_u32_e32 v5, 1, v7
	s_nop 0
	v_cndmask_b32_e32 v3, v3, v6, vcc
	v_mul_lo_u32 v6, v4, v3
	v_add_u32_e32 v4, v6, v4
	v_cmp_ne_u32_e32 vcc, v5, v4
	s_and_saveexec_b64 s[10:11], vcc
	s_xor_b64 s[10:11], exec, s[10:11]
	s_cbranch_execz .LBB0_544
	s_waitcnt lgkmcnt(0)
	v_add_u32_e32 v3, 1, v3
	v_mul_lo_u32 v3, v3, v2
	v_mov_b32_e32 v2, 0
	s_add_u32 s16, s66, 0x1bc3400
	s_addc_u32 s17, s67, 0
	global_load_dword v2, v2, s[16:17] sc1
	s_waitcnt vmcnt(0)
	v_cmp_lt_u32_e32 vcc, v2, v3
	s_and_saveexec_b64 s[12:13], vcc
	s_cbranch_execz .LBB0_543
	s_add_u32 s14, s66, 0x1bc0200
	s_addc_u32 s15, s67, 0
	s_mov_b32 s28, 1
	s_mov_b64 s[18:19], 0
	v_mov_b32_e32 v2, 0
	s_branch .LBB0_534

.LBB0_538:
	global_load_dword v4, v2, s[16:17] sc1
	s_add_i32 s28, s28, 1
	s_mov_b64 s[24:25], -1
	s_waitcnt vmcnt(0)
	v_cmp_ge_u32_e32 vcc, v4, v3
	s_orn2_b64 s[22:23], vcc, exec
	s_branch .LBB0_533

.LBB0_547:
	s_or_b64 exec, exec, s[12:13]
	v_cvt_f32_u32_e32 v5, v2
	s_waitcnt vmcnt(0)
	v_readfirstlane_b32 s10, v4
	s_add_u32 s12, s66, 0x1bc3400
	s_addc_u32 s13, s67, 0
	v_rcp_iflag_f32_e32 v5, v5
	v_add_u32_e32 v3, s10, v3
	v_add_u32_e32 v6, 1, v3
	s_mov_b64 s[14:15], -1
	v_mul_f32_e32 v4, 0x4f7ffffe, v5
	v_cvt_u32_f32_e32 v4, v4
	v_sub_u32_e32 v5, 0, v2
	v_mul_lo_u32 v5, v5, v4
	v_mul_hi_u32 v5, v4, v5
	v_add_u32_e32 v4, v4, v5
	v_mul_hi_u32 v4, v3, v4
	v_mul_lo_u32 v5, v4, v2
	v_sub_u32_e32 v3, v3, v5
	v_add_u32_e32 v7, 1, v4
	v_cmp_ge_u32_e32 vcc, v3, v2
	v_sub_u32_e32 v5, v3, v2
	s_nop 0
	v_cndmask_b32_e32 v4, v4, v7, vcc
	v_cndmask_b32_e32 v3, v3, v5, vcc
	v_add_u32_e32 v5, 1, v4
	v_cmp_ge_u32_e32 vcc, v3, v2
	s_nop 1
	v_cndmask_b32_e32 v4, v4, v5, vcc
	v_mul_lo_u32 v3, v2, v4
	v_add_u32_e32 v2, v3, v2
	v_cmp_ne_u32_e32 vcc, v6, v2
	v_mov_b32_e32 v4, v2
	v_mov_b64_e32 v[2:3], s[12:13]
	s_and_saveexec_b64 s[10:11], vcc
	s_cbranch_execz .LBB0_559
	v_mov_b32_e32 v2, 0
	global_load_dword v3, v2, s[12:13] sc1
	s_mov_b64 s[18:19], 0
	s_waitcnt vmcnt(0)
	v_cmp_lt_u32_e32 vcc, v3, v4
	s_and_saveexec_b64 s[16:17], vcc
	s_cbranch_execz .LBB0_558
	s_add_u32 s14, s66, 0x1bc0200
	s_addc_u32 s15, s67, 0
	s_mov_b32 s28, 1
	s_branch .LBB0_551

.LBB0_555:
	global_load_dword v3, v2, s[12:13] sc1
	s_add_i32 s28, s28, 1
	s_mov_b64 s[22:23], -1
	s_waitcnt vmcnt(0)
	v_cmp_ge_u32_e32 vcc, v3, v4
	s_orn2_b64 s[26:27], vcc, exec
	s_branch .LBB0_550

.LBB0_559:
	s_or_b64 exec, exec, s[10:11]
	s_and_saveexec_b64 s[10:11], s[14:15]
	s_cbranch_execz .LBB0_561
.LBB0_561:
	s_or_b64 exec, exec, s[10:11]
	s_mov_b64 s[10:11], exec
	v_mbcnt_lo_u32_b32 v2, s10, 0
	v_mbcnt_hi_u32_b32 v2, s11, v2
	v_cmp_eq_u32_e32 vcc, 0, v2
	s_waitcnt vmcnt(0)
	s_and_saveexec_b64 s[12:13], vcc
	s_cbranch_execz .LBB0_563
	s_bcnt1_i32_b64 s10, s[10:11]
	v_mov_b32_e32 v2, 0x2000
	v_mov_b32_e32 v3, s10
.LBB0_563:
	s_or_b64 exec, exec, s[12:13]
	s_waitcnt vmcnt(0)

.LBB0_678:
	s_or_b64 exec, exec, s[10:11]
	s_and_saveexec_b64 s[10:11], s[14:15]
	s_cbranch_execz .LBB0_680
.LBB0_680:
	s_or_b64 exec, exec, s[10:11]
	s_mov_b64 s[10:11], exec
	v_mbcnt_lo_u32_b32 v2, s10, 0
	v_mbcnt_hi_u32_b32 v2, s11, v2
	v_cmp_eq_u32_e32 vcc, 0, v2
	s_waitcnt vmcnt(0)
	s_and_saveexec_b64 s[12:13], vcc
	s_cbranch_execz .LBB0_682
	s_bcnt1_i32_b64 s10, s[10:11]
	v_mov_b32_e32 v2, 0x2000
	v_mov_b32_e32 v3, s10
.LBB0_682:
	s_or_b64 exec, exec, s[12:13]
	s_waitcnt vmcnt(0)

.LBB0_803:
	s_or_b64 exec, exec, s[10:11]
	s_and_saveexec_b64 s[10:11], s[14:15]
	s_cbranch_execz .LBB0_805
.LBB0_805:
	s_or_b64 exec, exec, s[10:11]
	s_mov_b64 s[10:11], exec
	v_mbcnt_lo_u32_b32 v2, s10, 0
	v_mbcnt_hi_u32_b32 v2, s11, v2
	v_cmp_eq_u32_e32 vcc, 0, v2
	s_waitcnt vmcnt(0)
	s_and_saveexec_b64 s[12:13], vcc
	s_cbranch_execz .LBB0_807
	s_bcnt1_i32_b64 s10, s[10:11]
	v_mov_b32_e32 v2, 0x2000
	v_mov_b32_e32 v3, s10
.LBB0_807:
	s_or_b64 exec, exec, s[12:13]
	s_waitcnt vmcnt(0)

.LBB0_878:
	s_or_b64 exec, exec, s[10:11]
	s_and_saveexec_b64 s[10:11], s[14:15]
	s_cbranch_execz .LBB0_880
.LBB0_880:
	s_or_b64 exec, exec, s[10:11]
	s_mov_b64 s[10:11], exec
	v_mbcnt_lo_u32_b32 v2, s10, 0
	v_mbcnt_hi_u32_b32 v2, s11, v2
	v_cmp_eq_u32_e32 vcc, 0, v2
	s_waitcnt vmcnt(0)
	s_and_saveexec_b64 s[12:13], vcc
	s_cbranch_execz .LBB0_882
	s_bcnt1_i32_b64 s10, s[10:11]
	v_mov_b32_e32 v2, 0x2000
	v_mov_b32_e32 v3, s10
.LBB0_882:
	s_or_b64 exec, exec, s[12:13]
	s_waitcnt vmcnt(0)

.LBB0_990:
	s_or_b64 exec, exec, s[10:11]
	s_and_saveexec_b64 s[10:11], s[14:15]
	s_cbranch_execz .LBB0_992
.LBB0_992:
	s_or_b64 exec, exec, s[10:11]
	s_mov_b64 s[10:11], exec
	v_mbcnt_lo_u32_b32 v2, s10, 0
	v_mbcnt_hi_u32_b32 v2, s11, v2
	v_cmp_eq_u32_e32 vcc, 0, v2
	s_waitcnt vmcnt(0)
	s_and_saveexec_b64 s[12:13], vcc
	s_cbranch_execz .LBB0_994
	s_bcnt1_i32_b64 s10, s[10:11]
	v_mov_b32_e32 v2, 0x2000
	v_mov_b32_e32 v3, s10
.LBB0_994:
	s_or_b64 exec, exec, s[12:13]
	s_waitcnt vmcnt(0)

.LBB0_1062:
	s_or_b64 exec, exec, s[10:11]
	s_and_saveexec_b64 s[10:11], s[14:15]
	s_cbranch_execz .LBB0_1064
.LBB0_1064:
	s_or_b64 exec, exec, s[10:11]
	s_mov_b64 s[10:11], exec
	v_mbcnt_lo_u32_b32 v2, s10, 0
	v_mbcnt_hi_u32_b32 v2, s11, v2
	v_cmp_eq_u32_e32 vcc, 0, v2
	s_waitcnt vmcnt(0)
	s_and_saveexec_b64 s[12:13], vcc
	s_cbranch_execz .LBB0_1066
	s_bcnt1_i32_b64 s10, s[10:11]
	v_mov_b32_e32 v2, 0x2000
	v_mov_b32_e32 v3, s10
.LBB0_1066:
	s_or_b64 exec, exec, s[12:13]
	s_waitcnt vmcnt(0)

.LBB0_1219:
	s_or_b64 exec, exec, s[10:11]
	s_and_saveexec_b64 s[10:11], s[14:15]
	s_cbranch_execz .LBB0_1221
.LBB0_1221:
	s_or_b64 exec, exec, s[10:11]
	s_mov_b64 s[10:11], exec
	v_mbcnt_lo_u32_b32 v2, s10, 0
	v_mbcnt_hi_u32_b32 v2, s11, v2
	v_cmp_eq_u32_e32 vcc, 0, v2
	s_waitcnt vmcnt(0)
	s_and_saveexec_b64 s[12:13], vcc
	s_cbranch_execz .LBB0_1223
	s_bcnt1_i32_b64 s10, s[10:11]
	v_mov_b32_e32 v2, 0x2000
	v_mov_b32_e32 v3, s10
.LBB0_1223:
	s_or_b64 exec, exec, s[12:13]
	s_waitcnt vmcnt(0)

.LBB0_1342:
	s_or_b64 exec, exec, s[10:11]
	s_and_saveexec_b64 s[10:11], s[14:15]
	s_cbranch_execz .LBB0_1344
.LBB0_1344:
	s_or_b64 exec, exec, s[10:11]
	s_mov_b64 s[10:11], exec
	v_mbcnt_lo_u32_b32 v2, s10, 0
	v_mbcnt_hi_u32_b32 v2, s11, v2
	v_cmp_eq_u32_e32 vcc, 0, v2
	s_waitcnt vmcnt(0)
	s_and_saveexec_b64 s[12:13], vcc
	s_cbranch_execz .LBB0_1346
	s_bcnt1_i32_b64 s10, s[10:11]
	v_mov_b32_e32 v2, 0x2000
	v_mov_b32_e32 v3, s10
.LBB0_1346:
	s_or_b64 exec, exec, s[12:13]
	s_waitcnt vmcnt(0)

.LBB0_1420:
	s_or_b64 exec, exec, s[10:11]
	s_and_saveexec_b64 s[10:11], s[14:15]
	s_cbranch_execz .LBB0_1422
.LBB0_1422:
	s_or_b64 exec, exec, s[10:11]
	s_mov_b64 s[10:11], exec
	v_mbcnt_lo_u32_b32 v2, s10, 0
	v_mbcnt_hi_u32_b32 v2, s11, v2
	v_cmp_eq_u32_e32 vcc, 0, v2
	s_waitcnt vmcnt(0)
	s_and_saveexec_b64 s[12:13], vcc
	s_cbranch_execz .LBB0_1424
	s_bcnt1_i32_b64 s10, s[10:11]
	v_mov_b32_e32 v2, 0x2000
	v_mov_b32_e32 v3, s10
.LBB0_1424:
	s_or_b64 exec, exec, s[12:13]
	s_waitcnt vmcnt(0)

.LBB0_1508:
	s_or_b64 exec, exec, s[10:11]
	s_and_saveexec_b64 s[10:11], s[14:15]
	s_cbranch_execz .LBB0_1510
.LBB0_1510:
	s_or_b64 exec, exec, s[10:11]
	s_mov_b64 s[10:11], exec
	v_mbcnt_lo_u32_b32 v2, s10, 0
	v_mbcnt_hi_u32_b32 v2, s11, v2
	v_cmp_eq_u32_e32 vcc, 0, v2
	s_waitcnt vmcnt(0)
	s_and_saveexec_b64 s[12:13], vcc
	s_cbranch_execz .LBB0_1512
	s_bcnt1_i32_b64 s10, s[10:11]
	v_mov_b32_e32 v2, 0x2000
	v_mov_b32_e32 v3, s10
.LBB0_1512:
	s_or_b64 exec, exec, s[12:13]
	s_waitcnt vmcnt(0)

.LBB0_1568:
	s_or_b64 exec, exec, s[12:13]
	v_cvt_f32_u32_e32 v6, v4
	s_waitcnt vmcnt(0)
	v_readfirstlane_b32 s3, v5
	v_sub_u32_e32 v5, 0, v4
	v_rcp_iflag_f32_e32 v6, v6
	v_add_u32_e32 v7, s3, v3
	v_mul_f32_e32 v6, 0x4f7ffffe, v6
	v_cvt_u32_f32_e32 v6, v6
	v_mul_lo_u32 v3, v5, v6
	v_mul_hi_u32 v3, v6, v3
	v_add_u32_e32 v3, v6, v3
	v_mul_hi_u32 v3, v7, v3
	v_mul_lo_u32 v5, v3, v4
	v_sub_u32_e32 v5, v7, v5
	v_add_u32_e32 v6, 1, v3
	v_cmp_ge_u32_e32 vcc, v5, v4
	s_nop 1
	v_cndmask_b32_e32 v3, v3, v6, vcc
	v_sub_u32_e32 v6, v5, v4
	v_cndmask_b32_e32 v5, v5, v6, vcc
	v_add_u32_e32 v6, 1, v3
	v_cmp_ge_u32_e32 vcc, v5, v4
	v_add_u32_e32 v5, 1, v7
	s_nop 0
	v_cndmask_b32_e32 v3, v3, v6, vcc
	v_mul_lo_u32 v6, v4, v3
	v_add_u32_e32 v4, v6, v4
	v_cmp_ne_u32_e32 vcc, v5, v4
	s_and_saveexec_b64 s[10:11], vcc
	s_xor_b64 s[10:11], exec, s[10:11]
	s_cbranch_execz .LBB0_1582
	s_waitcnt lgkmcnt(0)
	v_add_u32_e32 v3, 1, v3
	v_mul_lo_u32 v3, v3, v2
	v_mov_b32_e32 v2, 0
	s_add_u32 s16, s66, 0x1bc3400
	s_addc_u32 s17, s67, 0
	global_load_dword v2, v2, s[16:17] sc1
	s_waitcnt vmcnt(0)
	v_cmp_lt_u32_e32 vcc, v2, v3
	s_and_saveexec_b64 s[12:13], vcc
	s_cbranch_execz .LBB0_1581
	s_add_u32 s14, s66, 0x1bc0200
	s_addc_u32 s15, s67, 0
	s_mov_b32 s3, 1
	s_mov_b64 s[18:19], 0
	v_mov_b32_e32 v2, 0
	s_branch .LBB0_1572

.LBB0_1576:
	global_load_dword v4, v2, s[16:17] sc1
	s_add_i32 s3, s3, 1
	s_mov_b64 s[24:25], -1
	s_waitcnt vmcnt(0)
	v_cmp_ge_u32_e32 vcc, v4, v3
	s_orn2_b64 s[22:23], vcc, exec
	s_branch .LBB0_1571

.LBB0_1585:
	s_or_b64 exec, exec, s[12:13]
	v_cvt_f32_u32_e32 v5, v2
	s_waitcnt vmcnt(0)
	v_readfirstlane_b32 s3, v4
	s_add_u32 s12, s66, 0x1bc3400
	s_addc_u32 s13, s67, 0
	v_rcp_iflag_f32_e32 v5, v5
	v_add_u32_e32 v3, s3, v3
	v_add_u32_e32 v6, 1, v3
	s_mov_b64 s[14:15], -1
	v_mul_f32_e32 v4, 0x4f7ffffe, v5
	v_cvt_u32_f32_e32 v4, v4
	v_sub_u32_e32 v5, 0, v2
	v_mul_lo_u32 v5, v5, v4
	v_mul_hi_u32 v5, v4, v5
	v_add_u32_e32 v4, v4, v5
	v_mul_hi_u32 v4, v3, v4
	v_mul_lo_u32 v5, v4, v2
	v_sub_u32_e32 v3, v3, v5
	v_add_u32_e32 v7, 1, v4
	v_cmp_ge_u32_e32 vcc, v3, v2
	v_sub_u32_e32 v5, v3, v2
	s_nop 0
	v_cndmask_b32_e32 v4, v4, v7, vcc
	v_cndmask_b32_e32 v3, v3, v5, vcc
	v_add_u32_e32 v5, 1, v4
	v_cmp_ge_u32_e32 vcc, v3, v2
	s_nop 1
	v_cndmask_b32_e32 v4, v4, v5, vcc
	v_mul_lo_u32 v3, v2, v4
	v_add_u32_e32 v2, v3, v2
	v_cmp_ne_u32_e32 vcc, v6, v2
	v_mov_b32_e32 v4, v2
	v_mov_b64_e32 v[2:3], s[12:13]
	s_and_saveexec_b64 s[10:11], vcc
	s_cbranch_execz .LBB0_1597
	v_mov_b32_e32 v2, 0
	global_load_dword v3, v2, s[12:13] sc1
	s_mov_b64 s[18:19], 0
	s_waitcnt vmcnt(0)
	v_cmp_lt_u32_e32 vcc, v3, v4
	s_and_saveexec_b64 s[16:17], vcc
	s_cbranch_execz .LBB0_1596
	s_add_u32 s14, s66, 0x1bc0200
	s_addc_u32 s15, s67, 0
	s_mov_b32 s3, 1
	s_branch .LBB0_1589

.LBB0_1593:
	global_load_dword v3, v2, s[12:13] sc1
	s_add_i32 s3, s3, 1
	s_mov_b64 s[22:23], -1
	s_waitcnt vmcnt(0)
	v_cmp_ge_u32_e32 vcc, v3, v4
	s_orn2_b64 s[26:27], vcc, exec
	s_branch .LBB0_1588

.LBB0_1597:
	s_or_b64 exec, exec, s[10:11]
	s_and_saveexec_b64 s[10:11], s[14:15]
	s_cbranch_execz .LBB0_1599
.LBB0_1599:
	s_or_b64 exec, exec, s[10:11]
	s_mov_b64 s[10:11], exec
	v_mbcnt_lo_u32_b32 v2, s10, 0
	v_mbcnt_hi_u32_b32 v2, s11, v2
	v_cmp_eq_u32_e32 vcc, 0, v2
	s_waitcnt vmcnt(0)
	s_and_saveexec_b64 s[12:13], vcc
	s_cbranch_execz .LBB0_1601
	s_bcnt1_i32_b64 s3, s[10:11]
	v_mov_b32_e32 v2, 0x2000
	v_mov_b32_e32 v3, s3
.LBB0_1601:
	s_or_b64 exec, exec, s[12:13]
	s_waitcnt vmcnt(0)
